# c15 + scan variant-A waves write their partial outputs to LDS before the reduction arithmetic (LDS writes complete before the step barrier)
# baseline (speedup 1.0000x reference)
; __device__ __forceinline__ f32x16 mfma32(bf16x8 a, bf16x8 b, f32x16 c) { return __builtin_amdgcn_mfma_f32_32x32x16_bf16(a, b, c, 0, 0, 0); }
; #define SCAN_GLOAD(step, G_) do { const int gc_ = SCAN_GC(step); \
;         if (wave < 4) G_ = *(const u32x4*)(BVF + ((((size_t)gc_ * 4 + h) * 16 + sl) * 4 + wave) * 512); \
;         else if (wave == 4) G_ = *(const u32x4*)(DL + ((size_t)gc_ * 4 + h) * 256 + lane * 4); } while (0)
; #define SCAN_GSTORE(buf, G_) do { if (wave < 4) *(u32x4*)(vst + (((buf) * 4 + wave) * 64 + lane) * 16) = G_; \
;         else if (wave == 4) *(u32x4*)(dst + (buf) * 1024 + lane * 16) = G_; } while (0)
; __device__ __forceinline__ void phase_scan(const Args& a, unsigned char* smem, int tid, int lane, int wave) {
;     ...
;         const unsigned char* scb; unsigned scsg;
;         { const int q16s = sl * 16 + (lane & 15);
;           if (wave == 5) { if (lane < 16) { scb = (const unsigned char*)KDT + (size_t)h * 32768 + (size_t)q16s * 128; scsg = 131072u; }
;                            else if (lane < 32) { scb = (const unsigned char*)QE + (size_t)h * 512 + (size_t)(q16s >> 2) * 2048 + (q16s & 3) * 128; scsg = 131072u; }
;                            else if (lane < 36) { scb = (const unsigned char*)ATT + (size_t)h * 8192 + (size_t)(sl * 4 + lane - 32) * 128; scsg = 32768u; }
;                            else { scb = (const unsigned char*)DL + (size_t)h * 1024 + (lane & 7) * 128; scsg = 4096u; } }
;           else if (wave == 6) { scb = (const unsigned char*)(a.ws + WS_BVT) + (size_t)(h * 16 + sl) * 4096 + (size_t)(lane & 31) * 128; scsg = 262144u; }
;           else { scb = (const unsigned char*)DL + (size_t)h * 1024; scsg = 0u; } }
;         unsigned scA = 0u, scB = 0u;
;         __syncthreads();
;         SCAN_GLOAD(0, gcur); SCAN_GSTORE(0, gcur);
;         SCAN_GLOAD(1, gcur);
;         SCAN_LOAD(0, qeA, atA);
;         __syncthreads();
;         SCAN_LREAD(0, vB, dl);
;         __builtin_amdgcn_s_waitcnt(0x0F70);
;     ...
;             for (int i = 0; i < 16; ++i) S[i] *= dl[i >> 2][i & 3];
; #pragma unroll
;             for (int ks = 0; ks < 4; ++ks) S = mfma32(kdA[ks], vB[ks], S);
.Lscan_gb_done:
	v_lshrrev_b32_e32 v251, 5, v160
	v_lshlrev_b32_e32 v251, 4, v251
	s_lshl_b32 s41, s0, 7
	v_add_u32_e32 v251, s41, v251
	s_cmp_eq_u32 s17, 1
	s_cselect_b32 s40, 3, 0
	s_lshl_b32 s41, s15, 2
	s_add_i32 s40, s40, s41
	s_addk_i32 s40, 0x200
	s_lshl_b32 s41, s40, 17
	s_add_u32 s32, s20, s41
	s_addc_u32 s33, s21, 0
	s_lshl_b32 s41, s40, 18
	s_add_u32 s34, s48, s41
	s_addc_u32 s35, s49, 0
	s_lshl_b32 s41, s40, 12
	s_add_u32 s36, s46, s41
	s_addc_u32 s37, s47, 0
	global_load_dwordx4 v[16:19], v235, s[32:33]
	global_load_dwordx4 v[20:23], v235, s[32:33] offset:1024
	global_load_dwordx4 v[24:27], v235, s[32:33] offset:2048
	global_load_dwordx4 v[28:31], v235, s[32:33] offset:3072
	global_load_dwordx4 v[80:83], v234, s[34:35]
	global_load_dwordx4 v[84:87], v234, s[34:35] offset:1024
	global_load_dwordx4 v[88:91], v234, s[34:35] offset:2048
	global_load_dwordx4 v[92:95], v234, s[34:35] offset:3072
	global_load_dwordx4 v[144:147], v251, s[36:37]
	global_load_dwordx4 v[148:151], v251, s[36:37] offset:32
	global_load_dwordx4 v[152:155], v251, s[36:37] offset:64
	global_load_dwordx4 v[156:159], v251, s[36:37] offset:96
	s_cmp_eq_u32 s17, 1
	s_cselect_b32 s40, 2, 1
	s_lshl_b32 s41, s15, 2
	s_add_i32 s40, s40, s41
	s_addk_i32 s40, 0x200
	s_lshl_b32 s41, s40, 17
	s_add_u32 s32, s20, s41
	s_addc_u32 s33, s21, 0
	s_lshl_b32 s41, s40, 18
	s_add_u32 s34, s48, s41
	s_addc_u32 s35, s49, 0
	s_lshl_b32 s41, s40, 12
	s_add_u32 s36, s46, s41
	s_addc_u32 s37, s47, 0
	global_load_dwordx4 v[32:35], v235, s[32:33]
	global_load_dwordx4 v[36:39], v235, s[32:33] offset:1024
	global_load_dwordx4 v[40:43], v235, s[32:33] offset:2048
	global_load_dwordx4 v[44:47], v235, s[32:33] offset:3072
	global_load_dwordx4 v[96:99], v234, s[34:35]
	global_load_dwordx4 v[100:103], v234, s[34:35] offset:1024
	global_load_dwordx4 v[104:107], v234, s[34:35] offset:2048
	global_load_dwordx4 v[108:111], v234, s[34:35] offset:3072
	global_load_dwordx4 v[162:165], v251, s[36:37]
	global_load_dwordx4 v[166:169], v251, s[36:37] offset:32
	global_load_dwordx4 v[170:173], v251, s[36:37] offset:64
	global_load_dwordx4 v[174:177], v251, s[36:37] offset:96
	s_cmp_eq_u32 s17, 1
	s_cselect_b32 s40, 1, 2
	s_lshl_b32 s41, s15, 2
	s_add_i32 s40, s40, s41
	s_addk_i32 s40, 0x200
	s_lshl_b32 s41, s40, 17
	s_add_u32 s32, s20, s41
	s_addc_u32 s33, s21, 0
	s_lshl_b32 s41, s40, 18
	s_add_u32 s34, s48, s41
	s_addc_u32 s35, s49, 0
	s_lshl_b32 s41, s40, 12
	s_add_u32 s36, s46, s41
	s_addc_u32 s37, s47, 0
	global_load_dwordx4 v[48:51], v235, s[32:33]
	global_load_dwordx4 v[52:55], v235, s[32:33] offset:1024
	global_load_dwordx4 v[56:59], v235, s[32:33] offset:2048
	global_load_dwordx4 v[60:63], v235, s[32:33] offset:3072
	global_load_dwordx4 v[112:115], v234, s[34:35]
	global_load_dwordx4 v[116:119], v234, s[34:35] offset:1024
	global_load_dwordx4 v[120:123], v234, s[34:35] offset:2048
	global_load_dwordx4 v[124:127], v234, s[34:35] offset:3072
	global_load_dwordx4 v[178:181], v251, s[36:37]
	global_load_dwordx4 v[182:185], v251, s[36:37] offset:32
	global_load_dwordx4 v[186:189], v251, s[36:37] offset:64
	global_load_dwordx4 v[190:193], v251, s[36:37] offset:96
	s_cmp_eq_u32 s17, 1
	s_cselect_b32 s40, 0, 3
	s_lshl_b32 s41, s15, 2
	s_add_i32 s40, s40, s41
	s_addk_i32 s40, 0x200
	s_lshl_b32 s41, s40, 17
	s_add_u32 s32, s20, s41
	s_addc_u32 s33, s21, 0
	s_lshl_b32 s41, s40, 18
	s_add_u32 s34, s48, s41
	s_addc_u32 s35, s49, 0
	s_lshl_b32 s41, s40, 12
	s_add_u32 s36, s46, s41
	s_addc_u32 s37, s47, 0
	global_load_dwordx4 v[64:67], v235, s[32:33]
	global_load_dwordx4 v[68:71], v235, s[32:33] offset:1024
	global_load_dwordx4 v[72:75], v235, s[32:33] offset:2048
	global_load_dwordx4 v[76:79], v235, s[32:33] offset:3072
	global_load_dwordx4 v[128:131], v234, s[34:35]
	global_load_dwordx4 v[132:135], v234, s[34:35] offset:1024
	global_load_dwordx4 v[136:139], v234, s[34:35] offset:2048
	global_load_dwordx4 v[140:143], v234, s[34:35] offset:3072
	global_load_dwordx4 v[194:197], v251, s[36:37]
	global_load_dwordx4 v[198:201], v251, s[36:37] offset:32
	global_load_dwordx4 v[202:205], v251, s[36:37] offset:64
	global_load_dwordx4 v[206:209], v251, s[36:37] offset:96
	s_lshl_b32 s41, s0, 10
	v_add_u32_e32 v251, s41, v234
	s_waitcnt vmcnt(36)
	v_mfma_f32_32x32x16_bf16 v[0:15], v[16:19], v[80:83], 0
	v_mfma_f32_32x32x16_bf16 v[0:15], v[20:23], v[84:87], v[0:15]
	v_mfma_f32_32x32x16_bf16 v[0:15], v[24:27], v[88:91], v[0:15]
	v_mfma_f32_32x32x16_bf16 v[0:15], v[28:31], v[92:95], v[0:15]
	s_waitcnt vmcnt(24)
	s_nop 15
	v_pk_mul_f32 v[0:1], v[162:163], v[0:1]
	v_pk_mul_f32 v[2:3], v[164:165], v[2:3]
	v_pk_mul_f32 v[4:5], v[166:167], v[4:5]
	v_pk_mul_f32 v[6:7], v[168:169], v[6:7]
	v_pk_mul_f32 v[8:9], v[170:171], v[8:9]
	v_pk_mul_f32 v[10:11], v[172:173], v[10:11]
	v_pk_mul_f32 v[12:13], v[174:175], v[12:13]
	v_pk_mul_f32 v[14:15], v[176:177], v[14:15]
	s_nop 1
	v_mfma_f32_32x32x16_bf16 v[0:15], v[32:35], v[96:99], v[0:15]
	v_mfma_f32_32x32x16_bf16 v[0:15], v[36:39], v[100:103], v[0:15]
	v_mfma_f32_32x32x16_bf16 v[0:15], v[40:43], v[104:107], v[0:15]
	v_mfma_f32_32x32x16_bf16 v[0:15], v[44:47], v[108:111], v[0:15]
	s_waitcnt vmcnt(12)
	s_nop 15
	v_pk_mul_f32 v[0:1], v[178:179], v[0:1]
	v_pk_mul_f32 v[2:3], v[180:181], v[2:3]
	v_pk_mul_f32 v[4:5], v[182:183], v[4:5]
	v_pk_mul_f32 v[6:7], v[184:185], v[6:7]
	v_pk_mul_f32 v[8:9], v[186:187], v[8:9]
	v_pk_mul_f32 v[10:11], v[188:189], v[10:11]
	v_pk_mul_f32 v[12:13], v[190:191], v[12:13]
	v_pk_mul_f32 v[14:15], v[192:193], v[14:15]
	s_nop 1
	v_mfma_f32_32x32x16_bf16 v[0:15], v[48:51], v[112:115], v[0:15]
	v_mfma_f32_32x32x16_bf16 v[0:15], v[52:55], v[116:119], v[0:15]
	v_mfma_f32_32x32x16_bf16 v[0:15], v[56:59], v[120:123], v[0:15]
	v_mfma_f32_32x32x16_bf16 v[0:15], v[60:63], v[124:127], v[0:15]
	s_waitcnt vmcnt(0)
	s_nop 15
	v_pk_mul_f32 v[0:1], v[194:195], v[0:1]
	v_pk_mul_f32 v[2:3], v[196:197], v[2:3]
	v_pk_mul_f32 v[4:5], v[198:199], v[4:5]
	v_pk_mul_f32 v[6:7], v[200:201], v[6:7]
	v_pk_mul_f32 v[8:9], v[202:203], v[8:9]
	v_pk_mul_f32 v[10:11], v[204:205], v[10:11]
	v_pk_mul_f32 v[12:13], v[206:207], v[12:13]
	v_pk_mul_f32 v[14:15], v[208:209], v[14:15]
	s_nop 1
	v_mfma_f32_32x32x16_bf16 v[0:15], v[64:67], v[128:131], v[0:15]
	v_mfma_f32_32x32x16_bf16 v[0:15], v[68:71], v[132:135], v[0:15]
	v_mfma_f32_32x32x16_bf16 v[0:15], v[72:75], v[136:139], v[0:15]
	v_mfma_f32_32x32x16_bf16 v[0:15], v[76:79], v[140:143], v[0:15]
	s_nop 15
	s_nop 3
	s_mov_b32 s30, 0
	s_mov_b32 s42, 0
	s_min_u32 s42, s42, 0xff
	s_mul_i32 s42, s42, s29
	s_add_i32 s42, s42, s28
	v_mad_u64_u32 v[194:195], s[44:45], v238, s42, v[236:237]
	global_load_dwordx4 v[204:207], v[194:195], off
	s_mov_b32 s42, 1
	s_min_u32 s42, s42, 0xff
	s_mul_i32 s42, s42, s29
	s_add_i32 s42, s42, s28
	v_mad_u64_u32 v[194:195], s[44:45], v238, s42, v[236:237]
	global_load_dwordx4 v[208:211], v[194:195], off
	s_waitcnt vmcnt(0)
	s_barrier
; __device__ __forceinline__ void phase_scan(const Args& a, unsigned char* smem, int tid, int lane, int wave) {
;     ...
;         auto stepf = [&](const int step, unsigned& sc_issue, unsigned& sc_consume) __attribute__((always_inline)) {
;             const int nstep = step < 259 ? step + 1 : step, n2 = step < 258 ? step + 2 : 259;
;             SCAN_LOAD(nstep, nqe, nat);
;             SCAN_GLOAD(n2, gnxt);
;     ...
;             { int ss = step + SCOUT; ss = ss > 259 ? 259 : ss; const int gcs = SCAN_GC(ss); sc_issue = *(const unsigned*)(scb + (size_t)gcs * scsg); }
;     ...
;             const int gc = SCAN_GC(step); const size_t row0 = (size_t)gc * 64;
;             bf16x8 kdA[4];
;             { const bf16_t* kp = KDT + (((size_t)gc * 4 + h) * 8 + kb) * 2048 + lane * 8;
; #pragma unroll
;               for (int q = 0; q < 4; ++q) kdA[q] = *(const bf16x8*)(kp + 512 * q); }
;             const int rbuf = step & 1, nbuf = rbuf ^ 1;
;             if (gc < 512) {
;                 u32x4 s0, s1;
;                 s0.x = pk2(S[0], S[1]); s0.y = pk2(S[2], S[3]); s0.z = pk2(S[4], S[5]); s0.w = pk2(S[6], S[7]);
;                 s1.x = pk2(S[8], S[9]); s1.y = pk2(S[10], S[11]); s1.z = pk2(S[12], S[13]); s1.w = pk2(S[14], S[15]);
;                 const bf16x8 sb0 = __builtin_bit_cast(bf16x8, s0), sb1 = __builtin_bit_cast(bf16x8, s1);
;                 f32x16 o0, o1;
; #pragma unroll
;                 for (int i = 0; i < 16; ++i) { o0[i] = 0.f; o1[i] = 0.f; }
;                 o0 = mfma32(qeA[0], sb0, o0); o0 = mfma32(qeA[1], sb1, o0);
;                 o1 = mfma32(qeA[2], sb0, o1); o1 = mfma32(qeA[3], sb1, o1);
;                 const int w3 = wave & 3;
;                 const bf16x8 vs = w3 == 0 ? vB[0] : (w3 == 1 ? vB[1] : (w3 == 2 ? vB[2] : vB[3]));
;                 if (wave < 4) o0 = mfma32(atA, vs, o0); else o1 = mfma32(atA, vs, o1);
;                 unsigned* rb = red + (size_t)(rbuf * 8 + wave) * 1024 + lane; unsigned* rbx = red + (size_t)(rbuf * 8 + wave) * 1024 + (lane ^ 32);
; #pragma unroll
;                 for (int i = 0; i < 8; ++i) { unsigned* w_ = (i & 1) ? rbx : rb; w_[i * 64] = pk2(o0[2 * i], o0[2 * i + 1]); w_[512 + i * 64] = pk2(o1[2 * i], o1[2 * i + 1]); }
;             }
;             SCAN_GSTORE(nbuf, gcur);
;             __syncthreads();
;             if (gc < 512) {
	ds_write_b128 v239, v[204:207]
	ds_write_b128 v240, v[208:211]
	s_waitcnt lgkmcnt(0)
	s_barrier
	ds_read_b128 v[128:131], v246 offset:0
	ds_read_b128 v[132:135], v246 offset:1024
	ds_read_b128 v[136:139], v246 offset:2048
	ds_read_b128 v[140:143], v246 offset:3072
	ds_read_b128 v[196:199], v248 offset:0
	ds_read_b128 v[162:165], v247 offset:0
	ds_read_b128 v[166:169], v247 offset:32
	ds_read_b128 v[170:173], v247 offset:64
	ds_read_b128 v[174:177], v247 offset:96
	s_lshl_b32 s53, s29, 17
	s_lshl_b32 s54, s29, 15
	s_lshl_b32 s55, s29, 18
	s_ashr_i32 s56, s29, 31
	s_mov_b32 s40, 0
	s_mul_i32 s40, s40, s29
	s_add_i32 s40, s40, s28
	s_lshl_b32 s41, s40, 17
	s_add_u32 s32, s20, s41
	s_addc_u32 s33, s21, 0
	s_add_u32 s34, s22, s41
	s_addc_u32 s35, s23, 0
	s_lshl_b32 s41, s40, 15
	s_add_u32 s36, s24, s41
	s_addc_u32 s37, s25, 0
	s_add_i32 s42, s31, -2
	s_mul_i32 s42, s42, s29
	s_add_i32 s42, s42, s28
	v_mad_u64_u32 v[194:195], s[44:45], v238, s42, v[236:237]
	v_mul_lo_u32 v254, v238, s29
	v_ashrrev_i32_e32 v255, 31, v254
	s_lshl_b32 s40, s28, 18
	s_add_u32 s38, s26, s40
	s_addc_u32 s39, s27, 0
	global_load_dwordx4 v[204:207], v[194:195], off
	v_lshl_add_u64 v[194:195], v[194:195], 0, v[254:255]
	global_load_dwordx4 v[76:79], v235, s[32:33]
	global_load_dwordx4 v[80:83], v235, s[32:33] offset:1024
	global_load_dwordx4 v[84:87], v235, s[32:33] offset:2048
	global_load_dwordx4 v[88:91], v235, s[32:33] offset:3072
	global_load_dwordx4 v[56:59], v232, s[34:35] offset:-4096
	global_load_dwordx4 v[60:63], v232, s[34:35]
	global_load_dwordx4 v[64:67], v233, s[34:35] offset:-4096
	global_load_dwordx4 v[68:71], v233, s[34:35]
	global_load_dwordx4 v[72:75], v251, s[36:37]
	s_add_u32 s32, s32, s53
	s_addc_u32 s33, s33, s56
	s_add_u32 s34, s34, s53
	s_addc_u32 s35, s35, s56
	s_add_u32 s36, s36, s54
	s_addc_u32 s37, s37, s56
	global_load_dwordx4 v[208:211], v[194:195], off
	v_lshl_add_u64 v[194:195], v[194:195], 0, v[254:255]
	global_load_dwordx4 v[112:115], v235, s[32:33]
	global_load_dwordx4 v[116:119], v235, s[32:33] offset:1024
	global_load_dwordx4 v[120:123], v235, s[32:33] offset:2048
	global_load_dwordx4 v[124:127], v235, s[32:33] offset:3072
	global_load_dwordx4 v[92:95], v232, s[34:35] offset:-4096
	global_load_dwordx4 v[96:99], v232, s[34:35]
	global_load_dwordx4 v[100:103], v233, s[34:35] offset:-4096
	global_load_dwordx4 v[104:107], v233, s[34:35]
	global_load_dwordx4 v[108:111], v251, s[36:37]
	s_add_u32 s32, s32, s53
	s_addc_u32 s33, s33, s56
	s_add_u32 s34, s34, s53
	s_addc_u32 s35, s35, s56
	s_add_u32 s36, s36, s54
	s_addc_u32 s37, s37, s56
	s_waitcnt lgkmcnt(0)
	s_barrier
	s_cmp_lt_u32 s0, 4
	s_cbranch_scc0 .Lscan_pathB
	s_waitcnt vmcnt(10)
	ds_write_b128 v239, v[204:207]
	global_load_dwordx4 v[204:207], v[194:195], off
	v_lshl_add_u64 v[194:195], v[194:195], 0, v[254:255]
	v_cvt_pk_bf16_f32 v48, v0, v1
	v_cvt_pk_bf16_f32 v49, v2, v3
	v_cvt_pk_bf16_f32 v50, v4, v5
	v_cvt_pk_bf16_f32 v51, v6, v7
	v_cvt_pk_bf16_f32 v52, v8, v9
	v_cvt_pk_bf16_f32 v53, v10, v11
	v_cvt_pk_bf16_f32 v54, v12, v13
	v_cvt_pk_bf16_f32 v55, v14, v15
	v_mfma_f32_32x32x16_bf16 v[16:31], v[56:59], v[48:51], 0
	v_pk_mul_f32 v[0:1], v[162:163], v[0:1]
	v_pk_mul_f32 v[2:3], v[164:165], v[2:3]
	v_pk_mul_f32 v[4:5], v[166:167], v[4:5]
	v_mfma_f32_32x32x16_bf16 v[32:47], v[64:67], v[48:51], 0
	v_pk_mul_f32 v[6:7], v[168:169], v[6:7]
	v_pk_mul_f32 v[8:9], v[170:171], v[8:9]
	v_pk_mul_f32 v[10:11], v[172:173], v[10:11]
	v_mfma_f32_32x32x16_bf16 v[16:31], v[60:63], v[52:55], v[16:31]
	v_pk_mul_f32 v[12:13], v[174:175], v[12:13]
	v_pk_mul_f32 v[14:15], v[176:177], v[14:15]
	v_mfma_f32_32x32x16_bf16 v[32:47], v[68:71], v[52:55], v[32:47]
	v_mfma_f32_32x32x16_bf16 v[16:31], v[72:75], v[196:199], v[16:31]
	v_mfma_f32_32x32x16_bf16 v[0:15], v[76:79], v[128:131], v[0:15]
	v_mfma_f32_32x32x16_bf16 v[0:15], v[80:83], v[132:135], v[0:15]
	v_mfma_f32_32x32x16_bf16 v[0:15], v[84:87], v[136:139], v[0:15]
	v_mfma_f32_32x32x16_bf16 v[0:15], v[88:91], v[140:143], v[0:15]
	ds_read_b128 v[144:147], v246 offset:4096
	global_load_dwordx4 v[76:79], v235, s[32:33]
	ds_read_b128 v[148:151], v246 offset:5120
	ds_read_b128 v[152:155], v246 offset:6144
	ds_read_b128 v[156:159], v246 offset:7168
	ds_read_b128 v[200:203], v248 offset:4096
	global_load_dwordx4 v[80:83], v235, s[32:33] offset:1024
	ds_read_b128 v[178:181], v247 offset:1024
	ds_read_b128 v[182:185], v247 offset:1056
	ds_read_b128 v[186:189], v247 offset:1088
	ds_read_b128 v[190:193], v247 offset:1120
	global_load_dwordx4 v[84:87], v235, s[32:33] offset:2048
	v_cvt_pk_bf16_f32 v16, v16, v17
	v_cvt_pk_bf16_f32 v18, v18, v19
	v_cvt_pk_bf16_f32 v20, v20, v21
	global_load_dwordx4 v[88:91], v235, s[32:33] offset:3072
	v_cvt_pk_bf16_f32 v22, v22, v23
	v_cvt_pk_bf16_f32 v24, v24, v25
	v_cvt_pk_bf16_f32 v26, v26, v27
	v_cvt_pk_bf16_f32 v28, v28, v29
	global_load_dwordx4 v[56:59], v232, s[34:35] offset:-4096
	v_cvt_pk_bf16_f32 v30, v30, v31
	ds_write2st64_b32 v241, v16, v20 offset0:0 offset1:2
	ds_write2st64_b32 v242, v18, v22 offset0:1 offset1:3
	ds_write2st64_b32 v241, v24, v28 offset0:4 offset1:6
	global_load_dwordx4 v[60:63], v232, s[34:35]
	ds_write2st64_b32 v242, v26, v30 offset0:5 offset1:7
	v_cvt_pk_bf16_f32 v32, v32, v33
	v_cvt_pk_bf16_f32 v34, v34, v35
	global_load_dwordx4 v[64:67], v233, s[34:35] offset:-4096
	v_cvt_pk_bf16_f32 v36, v36, v37
	v_cvt_pk_bf16_f32 v38, v38, v39
	v_cvt_pk_bf16_f32 v40, v40, v41
	v_cvt_pk_bf16_f32 v42, v42, v43
	global_load_dwordx4 v[68:71], v233, s[34:35]
	v_cvt_pk_bf16_f32 v44, v44, v45
	v_cvt_pk_bf16_f32 v46, v46, v47
	ds_write2st64_b32 v243, v32, v36 offset0:0 offset1:2
	ds_write2st64_b32 v244, v34, v38 offset0:1 offset1:3
	global_load_dwordx4 v[72:75], v251, s[36:37]
	ds_write2st64_b32 v243, v40, v44 offset0:4 offset1:6
	ds_write2st64_b32 v244, v42, v46 offset0:5 offset1:7
	s_add_u32 s32, s32, s53
	s_addc_u32 s33, s33, s56
	s_add_u32 s34, s34, s53
	s_addc_u32 s35, s35, s56
	s_add_u32 s36, s36, s54
	s_addc_u32 s37, s37, s56
	s_waitcnt lgkmcnt(0)
	s_barrier
; __device__ __forceinline__ void phase_scan(const Args& a, unsigned char* smem, int tid, int lane, int wave) {
;     ...
;             if (gc < 512) {
;                 u32x4 s0, s1;
;                 s0.x = pk2(S[0], S[1]); s0.y = pk2(S[2], S[3]); s0.z = pk2(S[4], S[5]); s0.w = pk2(S[6], S[7]);
;                 s1.x = pk2(S[8], S[9]); s1.y = pk2(S[10], S[11]); s1.z = pk2(S[12], S[13]); s1.w = pk2(S[14], S[15]);
;                 const bf16x8 sb0 = __builtin_bit_cast(bf16x8, s0), sb1 = __builtin_bit_cast(bf16x8, s1);
;                 f32x16 o0, o1;
; #pragma unroll
;                 for (int i = 0; i < 16; ++i) { o0[i] = 0.f; o1[i] = 0.f; }
;                 o0 = mfma32(qeA[0], sb0, o0); o0 = mfma32(qeA[1], sb1, o0);
;                 o1 = mfma32(qeA[2], sb0, o1); o1 = mfma32(qeA[3], sb1, o1);
;                 const int w3 = wave & 3;
;                 const bf16x8 vs = w3 == 0 ? vB[0] : (w3 == 1 ? vB[1] : (w3 == 2 ? vB[2] : vB[3]));
;                 if (wave < 4) o0 = mfma32(atA, vs, o0); else o1 = mfma32(atA, vs, o1);
;                 unsigned* rb = red + (size_t)(rbuf * 8 + wave) * 1024 + lane; unsigned* rbx = red + (size_t)(rbuf * 8 + wave) * 1024 + (lane ^ 32);
; #pragma unroll
;                 for (int i = 0; i < 8; ++i) { unsigned* w_ = (i & 1) ? rbx : rb; w_[i * 64] = pk2(o0[2 * i], o0[2 * i + 1]); w_[512 + i * 64] = pk2(o1[2 * i], o1[2 * i + 1]); }
;             }
;             SCAN_GSTORE(nbuf, gcur);
;             __syncthreads();
;             if (gc < 512) {
;                 const int tp = tid >> 4, dv2 = (tid & 15) * 2, t = tp * 2, mt = t >> 5, tl = t & 31, pi = 2 * (tl >> 3) + ((tl & 3) >> 1), ln = ((tl >> 2) & 1) * 32 + dv2;
;                 const unsigned* rp = red + (size_t)rbuf * 8192 + (mt * 8 + pi) * 64 + (ln ^ ((pi & 1) << 5));
;                 float a0 = 0.f, a1 = 0.f, b0 = 0.f, b1 = 0.f;
; #pragma unroll
;                 for (int w = 0; w < 8; ++w) { const u32x2 v = *(const u32x2*)(rp + w * 1024); a0 += bflo(v.x); b0 += bfhi(v.x); a1 += bflo(v.y); b1 += bfhi(v.y); }
;                 bf16_t* op = O + (row0 + t) * 2048 + h * 512 + sl * 32 + dv2;
;                 *(unsigned*)op = pk2(a0, a1); *(unsigned*)(op + 2048) = pk2(b0, b1);
;             }
;             f32x4 ndl[4]; bf16x8 nvB[4];
;             SCAN_LREAD(nbuf, nvB, ndl);
; #pragma unroll
;             for (int i = 0; i < 16; ++i) S[i] *= dl[i >> 2][i & 3];
; #pragma unroll
	s_waitcnt vmcnt(10)
	ds_write_b128 v240, v[208:211]
	global_load_dwordx4 v[208:211], v[194:195], off
	v_lshl_add_u64 v[194:195], v[194:195], 0, v[254:255]
	v_cvt_pk_bf16_f32 v48, v0, v1
	v_cvt_pk_bf16_f32 v49, v2, v3
	v_cvt_pk_bf16_f32 v50, v4, v5
	v_cvt_pk_bf16_f32 v51, v6, v7
	v_cvt_pk_bf16_f32 v52, v8, v9
	v_cvt_pk_bf16_f32 v53, v10, v11
	v_cvt_pk_bf16_f32 v54, v12, v13
	v_cvt_pk_bf16_f32 v55, v14, v15
	v_mfma_f32_32x32x16_bf16 v[16:31], v[92:95], v[48:51], 0
	v_pk_mul_f32 v[0:1], v[178:179], v[0:1]
	v_pk_mul_f32 v[2:3], v[180:181], v[2:3]
	v_pk_mul_f32 v[4:5], v[182:183], v[4:5]
	v_mfma_f32_32x32x16_bf16 v[32:47], v[100:103], v[48:51], 0
	v_pk_mul_f32 v[6:7], v[184:185], v[6:7]
	v_pk_mul_f32 v[8:9], v[186:187], v[8:9]
	v_pk_mul_f32 v[10:11], v[188:189], v[10:11]
	v_mfma_f32_32x32x16_bf16 v[16:31], v[96:99], v[52:55], v[16:31]
	v_pk_mul_f32 v[12:13], v[190:191], v[12:13]
	v_pk_mul_f32 v[14:15], v[192:193], v[14:15]
	v_mfma_f32_32x32x16_bf16 v[32:47], v[104:107], v[52:55], v[32:47]
	v_mfma_f32_32x32x16_bf16 v[16:31], v[108:111], v[200:203], v[16:31]
	v_mfma_f32_32x32x16_bf16 v[0:15], v[112:115], v[144:147], v[0:15]
	v_mfma_f32_32x32x16_bf16 v[0:15], v[116:119], v[148:151], v[0:15]
	v_mfma_f32_32x32x16_bf16 v[0:15], v[120:123], v[152:155], v[0:15]
	v_mfma_f32_32x32x16_bf16 v[0:15], v[124:127], v[156:159], v[0:15]
	ds_read2st64_b64 v[212:215], v245 offset0:0 offset1:8
	ds_read2st64_b64 v[216:219], v245 offset0:16 offset1:24
	ds_read2st64_b64 v[220:223], v245 offset0:32 offset1:40
	ds_read2st64_b64 v[224:227], v245 offset0:48 offset1:56
	ds_read_b128 v[128:131], v246 offset:0
	global_load_dwordx4 v[112:115], v235, s[32:33]
	ds_read_b128 v[132:135], v246 offset:1024
	ds_read_b128 v[136:139], v246 offset:2048
	ds_read_b128 v[140:143], v246 offset:3072
	ds_read_b128 v[196:199], v248 offset:0
	ds_read_b128 v[162:165], v247 offset:0
	ds_read_b128 v[166:169], v247 offset:32
	ds_read_b128 v[170:173], v247 offset:64
	ds_read_b128 v[174:177], v247 offset:96
	v_cvt_pk_bf16_f32 v16, v16, v17
	v_cvt_pk_bf16_f32 v18, v18, v19
	global_load_dwordx4 v[116:119], v235, s[32:33] offset:1024
	v_cvt_pk_bf16_f32 v20, v20, v21
	v_cvt_pk_bf16_f32 v22, v22, v23
	v_cvt_pk_bf16_f32 v24, v24, v25
	v_cvt_pk_bf16_f32 v26, v26, v27
	v_cvt_pk_bf16_f32 v28, v28, v29
	v_cvt_pk_bf16_f32 v30, v30, v31
	ds_write2st64_b32 v241, v16, v20 offset0:128 offset1:130
	ds_write2st64_b32 v242, v18, v22 offset0:129 offset1:131
	ds_write2st64_b32 v241, v24, v28 offset0:132 offset1:134
	ds_write2st64_b32 v242, v26, v30 offset0:133 offset1:135
	v_cvt_pk_bf16_f32 v32, v32, v33
	global_load_dwordx4 v[120:123], v235, s[32:33] offset:2048
	v_cvt_pk_bf16_f32 v34, v34, v35
	v_cvt_pk_bf16_f32 v36, v36, v37
	v_cvt_pk_bf16_f32 v38, v38, v39
	v_cvt_pk_bf16_f32 v40, v40, v41
	v_cvt_pk_bf16_f32 v42, v42, v43
	v_cvt_pk_bf16_f32 v44, v44, v45
	v_cvt_pk_bf16_f32 v46, v46, v47
	ds_write2st64_b32 v243, v32, v36 offset0:128 offset1:130
	ds_write2st64_b32 v244, v34, v38 offset0:129 offset1:131
	ds_write2st64_b32 v243, v40, v44 offset0:132 offset1:134
	global_load_dwordx4 v[124:127], v235, s[32:33] offset:3072
	ds_write2st64_b32 v244, v42, v46 offset0:133 offset1:135
	s_waitcnt lgkmcnt(15)
	v_lshlrev_b32_e32 v229, 16, v213
	v_lshlrev_b32_e32 v228, 16, v212
	v_pk_add_f32 v[228:229], v[228:229], 0 op_sel_hi:[1,0]
	v_and_b32_e32 v231, 0xffff0000, v213
	v_and_b32_e32 v230, 0xffff0000, v212
	v_pk_add_f32 v[230:231], v[230:231], 0 op_sel_hi:[1,0]
	v_lshlrev_b32_e32 v49, 16, v215
	v_lshlrev_b32_e32 v48, 16, v214
	v_pk_add_f32 v[228:229], v[228:229], v[48:49]
	global_load_dwordx4 v[92:95], v232, s[34:35] offset:-4096
	v_and_b32_e32 v215, 0xffff0000, v215
	v_and_b32_e32 v214, 0xffff0000, v214
	v_pk_add_f32 v[230:231], v[230:231], v[214:215]
	s_waitcnt lgkmcnt(15)
	v_lshlrev_b32_e32 v49, 16, v217
	v_lshlrev_b32_e32 v48, 16, v216
	v_pk_add_f32 v[228:229], v[228:229], v[48:49]
	v_and_b32_e32 v217, 0xffff0000, v217
	v_and_b32_e32 v216, 0xffff0000, v216
	v_pk_add_f32 v[230:231], v[230:231], v[216:217]
	v_lshlrev_b32_e32 v49, 16, v219
	global_load_dwordx4 v[96:99], v232, s[34:35]
	v_lshlrev_b32_e32 v48, 16, v218
	v_pk_add_f32 v[228:229], v[228:229], v[48:49]
	v_and_b32_e32 v219, 0xffff0000, v219
	v_and_b32_e32 v218, 0xffff0000, v218
	v_pk_add_f32 v[230:231], v[230:231], v[218:219]
	s_waitcnt lgkmcnt(15)
	v_lshlrev_b32_e32 v49, 16, v221
	v_lshlrev_b32_e32 v48, 16, v220
	v_pk_add_f32 v[228:229], v[228:229], v[48:49]
	v_and_b32_e32 v221, 0xffff0000, v221
	global_load_dwordx4 v[100:103], v233, s[34:35] offset:-4096
	v_and_b32_e32 v220, 0xffff0000, v220
	v_pk_add_f32 v[230:231], v[230:231], v[220:221]
	v_lshlrev_b32_e32 v49, 16, v223
	v_lshlrev_b32_e32 v48, 16, v222
	v_pk_add_f32 v[228:229], v[228:229], v[48:49]
	v_and_b32_e32 v223, 0xffff0000, v223
	v_and_b32_e32 v222, 0xffff0000, v222
	v_pk_add_f32 v[230:231], v[230:231], v[222:223]
	s_waitcnt lgkmcnt(15)
	v_lshlrev_b32_e32 v49, 16, v225
	v_lshlrev_b32_e32 v48, 16, v224
	global_load_dwordx4 v[104:107], v233, s[34:35]
	v_pk_add_f32 v[228:229], v[228:229], v[48:49]
	v_and_b32_e32 v225, 0xffff0000, v225
	v_and_b32_e32 v224, 0xffff0000, v224
	v_pk_add_f32 v[230:231], v[230:231], v[224:225]
	v_lshlrev_b32_e32 v49, 16, v227
	v_lshlrev_b32_e32 v48, 16, v226
	v_pk_add_f32 v[228:229], v[228:229], v[48:49]
	v_and_b32_e32 v227, 0xffff0000, v227
	v_and_b32_e32 v226, 0xffff0000, v226
	v_pk_add_f32 v[230:231], v[230:231], v[226:227]
	global_load_dwordx4 v[108:111], v251, s[36:37]
	v_cvt_pk_bf16_f32 v228, v228, v229
	v_cvt_pk_bf16_f32 v230, v230, v231
	global_store_dword v249, v228, s[38:39]
	global_store_dword v250, v230, s[38:39]
	s_add_u32 s38, s38, s55
	s_addc_u32 s39, s39, s56
	s_add_u32 s32, s32, s53
	s_addc_u32 s33, s33, s56
	s_add_u32 s34, s34, s53
	s_addc_u32 s35, s35, s56
	s_add_u32 s36, s36, s54
	s_addc_u32 s37, s37, s56
	s_waitcnt lgkmcnt(0)
	s_barrier
; __device__ __forceinline__ void phase_scan(const Args& a, unsigned char* smem, int tid, int lane, int wave) {
;     ...
;             if (gc < 512) {
;                 u32x4 s0, s1;
;                 s0.x = pk2(S[0], S[1]); s0.y = pk2(S[2], S[3]); s0.z = pk2(S[4], S[5]); s0.w = pk2(S[6], S[7]);
;                 s1.x = pk2(S[8], S[9]); s1.y = pk2(S[10], S[11]); s1.z = pk2(S[12], S[13]); s1.w = pk2(S[14], S[15]);
;                 const bf16x8 sb0 = __builtin_bit_cast(bf16x8, s0), sb1 = __builtin_bit_cast(bf16x8, s1);
;                 f32x16 o0, o1;
; #pragma unroll
;                 for (int i = 0; i < 16; ++i) { o0[i] = 0.f; o1[i] = 0.f; }
;                 o0 = mfma32(qeA[0], sb0, o0); o0 = mfma32(qeA[1], sb1, o0);
;                 o1 = mfma32(qeA[2], sb0, o1); o1 = mfma32(qeA[3], sb1, o1);
;                 const int w3 = wave & 3;
;                 const bf16x8 vs = w3 == 0 ? vB[0] : (w3 == 1 ? vB[1] : (w3 == 2 ? vB[2] : vB[3]));
;                 if (wave < 4) o0 = mfma32(atA, vs, o0); else o1 = mfma32(atA, vs, o1);
;                 unsigned* rb = red + (size_t)(rbuf * 8 + wave) * 1024 + lane; unsigned* rbx = red + (size_t)(rbuf * 8 + wave) * 1024 + (lane ^ 32);
; #pragma unroll
;                 for (int i = 0; i < 8; ++i) { unsigned* w_ = (i & 1) ? rbx : rb; w_[i * 64] = pk2(o0[2 * i], o0[2 * i + 1]); w_[512 + i * 64] = pk2(o1[2 * i], o1[2 * i + 1]); }
;             }
;             SCAN_GSTORE(nbuf, gcur);
;             __syncthreads();
;             if (gc < 512) {
;                 const int tp = tid >> 4, dv2 = (tid & 15) * 2, t = tp * 2, mt = t >> 5, tl = t & 31, pi = 2 * (tl >> 3) + ((tl & 3) >> 1), ln = ((tl >> 2) & 1) * 32 + dv2;
;                 const unsigned* rp = red + (size_t)rbuf * 8192 + (mt * 8 + pi) * 64 + (ln ^ ((pi & 1) << 5));
;                 float a0 = 0.f, a1 = 0.f, b0 = 0.f, b1 = 0.f;
; #pragma unroll
;                 for (int w = 0; w < 8; ++w) { const u32x2 v = *(const u32x2*)(rp + w * 1024); a0 += bflo(v.x); b0 += bfhi(v.x); a1 += bflo(v.y); b1 += bfhi(v.y); }
;                 bf16_t* op = O + (row0 + t) * 2048 + h * 512 + sl * 32 + dv2;
;                 *(unsigned*)op = pk2(a0, a1); *(unsigned*)(op + 2048) = pk2(b0, b1);
;             }
;             f32x4 ndl[4]; bf16x8 nvB[4];
;             SCAN_LREAD(nbuf, nvB, ndl);
; #pragma unroll
;             for (int i = 0; i < 16; ++i) S[i] *= dl[i >> 2][i & 3];
; #pragma unroll
	s_waitcnt vmcnt(12)
	ds_write_b128 v239, v[204:207]
	global_load_dwordx4 v[204:207], v[194:195], off
	v_lshl_add_u64 v[194:195], v[194:195], 0, v[254:255]
	v_cvt_pk_bf16_f32 v48, v0, v1
	v_cvt_pk_bf16_f32 v49, v2, v3
	v_cvt_pk_bf16_f32 v50, v4, v5
	v_cvt_pk_bf16_f32 v51, v6, v7
	v_cvt_pk_bf16_f32 v52, v8, v9
	v_cvt_pk_bf16_f32 v53, v10, v11
	v_cvt_pk_bf16_f32 v54, v12, v13
	v_cvt_pk_bf16_f32 v55, v14, v15
	v_mfma_f32_32x32x16_bf16 v[16:31], v[56:59], v[48:51], 0
	v_pk_mul_f32 v[0:1], v[162:163], v[0:1]
	v_pk_mul_f32 v[2:3], v[164:165], v[2:3]
	v_pk_mul_f32 v[4:5], v[166:167], v[4:5]
	v_mfma_f32_32x32x16_bf16 v[32:47], v[64:67], v[48:51], 0
	v_pk_mul_f32 v[6:7], v[168:169], v[6:7]
	v_pk_mul_f32 v[8:9], v[170:171], v[8:9]
	v_pk_mul_f32 v[10:11], v[172:173], v[10:11]
	v_mfma_f32_32x32x16_bf16 v[16:31], v[60:63], v[52:55], v[16:31]
	v_pk_mul_f32 v[12:13], v[174:175], v[12:13]
	v_pk_mul_f32 v[14:15], v[176:177], v[14:15]
	v_mfma_f32_32x32x16_bf16 v[32:47], v[68:71], v[52:55], v[32:47]
	v_mfma_f32_32x32x16_bf16 v[16:31], v[72:75], v[196:199], v[16:31]
	v_mfma_f32_32x32x16_bf16 v[0:15], v[76:79], v[128:131], v[0:15]
	v_mfma_f32_32x32x16_bf16 v[0:15], v[80:83], v[132:135], v[0:15]
	v_mfma_f32_32x32x16_bf16 v[0:15], v[84:87], v[136:139], v[0:15]
	v_mfma_f32_32x32x16_bf16 v[0:15], v[88:91], v[140:143], v[0:15]
	ds_read2st64_b64 v[212:215], v245 offset0:64 offset1:72
	ds_read2st64_b64 v[216:219], v245 offset0:80 offset1:88
	ds_read2st64_b64 v[220:223], v245 offset0:96 offset1:104
	ds_read2st64_b64 v[224:227], v245 offset0:112 offset1:120
	ds_read_b128 v[144:147], v246 offset:4096
	global_load_dwordx4 v[76:79], v235, s[32:33]
	ds_read_b128 v[148:151], v246 offset:5120
	ds_read_b128 v[152:155], v246 offset:6144
	ds_read_b128 v[156:159], v246 offset:7168
	ds_read_b128 v[200:203], v248 offset:4096
	ds_read_b128 v[178:181], v247 offset:1024
	ds_read_b128 v[182:185], v247 offset:1056
	ds_read_b128 v[186:189], v247 offset:1088
	ds_read_b128 v[190:193], v247 offset:1120
	v_cvt_pk_bf16_f32 v16, v16, v17
	v_cvt_pk_bf16_f32 v18, v18, v19
	global_load_dwordx4 v[80:83], v235, s[32:33] offset:1024
	v_cvt_pk_bf16_f32 v20, v20, v21
	v_cvt_pk_bf16_f32 v22, v22, v23
	v_cvt_pk_bf16_f32 v24, v24, v25
	v_cvt_pk_bf16_f32 v26, v26, v27
	v_cvt_pk_bf16_f32 v28, v28, v29
	v_cvt_pk_bf16_f32 v30, v30, v31
	ds_write2st64_b32 v241, v16, v20 offset0:0 offset1:2
	ds_write2st64_b32 v242, v18, v22 offset0:1 offset1:3
	ds_write2st64_b32 v241, v24, v28 offset0:4 offset1:6
	ds_write2st64_b32 v242, v26, v30 offset0:5 offset1:7
	v_cvt_pk_bf16_f32 v32, v32, v33
	global_load_dwordx4 v[84:87], v235, s[32:33] offset:2048
	v_cvt_pk_bf16_f32 v34, v34, v35
	v_cvt_pk_bf16_f32 v36, v36, v37
	v_cvt_pk_bf16_f32 v38, v38, v39
	v_cvt_pk_bf16_f32 v40, v40, v41
	v_cvt_pk_bf16_f32 v42, v42, v43
	v_cvt_pk_bf16_f32 v44, v44, v45
	v_cvt_pk_bf16_f32 v46, v46, v47
	ds_write2st64_b32 v243, v32, v36 offset0:0 offset1:2
	ds_write2st64_b32 v244, v34, v38 offset0:1 offset1:3
	ds_write2st64_b32 v243, v40, v44 offset0:4 offset1:6
	global_load_dwordx4 v[88:91], v235, s[32:33] offset:3072
	ds_write2st64_b32 v244, v42, v46 offset0:5 offset1:7
	s_waitcnt lgkmcnt(15)
	v_lshlrev_b32_e32 v229, 16, v213
	v_lshlrev_b32_e32 v228, 16, v212
	v_pk_add_f32 v[228:229], v[228:229], 0 op_sel_hi:[1,0]
	v_and_b32_e32 v231, 0xffff0000, v213
	v_and_b32_e32 v230, 0xffff0000, v212
	v_pk_add_f32 v[230:231], v[230:231], 0 op_sel_hi:[1,0]
	v_lshlrev_b32_e32 v49, 16, v215
	v_lshlrev_b32_e32 v48, 16, v214
	v_pk_add_f32 v[228:229], v[228:229], v[48:49]
	global_load_dwordx4 v[56:59], v232, s[34:35] offset:-4096
	v_and_b32_e32 v215, 0xffff0000, v215
	v_and_b32_e32 v214, 0xffff0000, v214
	v_pk_add_f32 v[230:231], v[230:231], v[214:215]
	s_waitcnt lgkmcnt(15)
	v_lshlrev_b32_e32 v49, 16, v217
	v_lshlrev_b32_e32 v48, 16, v216
	v_pk_add_f32 v[228:229], v[228:229], v[48:49]
	v_and_b32_e32 v217, 0xffff0000, v217
	v_and_b32_e32 v216, 0xffff0000, v216
	v_pk_add_f32 v[230:231], v[230:231], v[216:217]
	v_lshlrev_b32_e32 v49, 16, v219
	global_load_dwordx4 v[60:63], v232, s[34:35]
	v_lshlrev_b32_e32 v48, 16, v218
	v_pk_add_f32 v[228:229], v[228:229], v[48:49]
	v_and_b32_e32 v219, 0xffff0000, v219
	v_and_b32_e32 v218, 0xffff0000, v218
	v_pk_add_f32 v[230:231], v[230:231], v[218:219]
	s_waitcnt lgkmcnt(15)
	v_lshlrev_b32_e32 v49, 16, v221
	v_lshlrev_b32_e32 v48, 16, v220
	v_pk_add_f32 v[228:229], v[228:229], v[48:49]
	v_and_b32_e32 v221, 0xffff0000, v221
	global_load_dwordx4 v[64:67], v233, s[34:35] offset:-4096
	v_and_b32_e32 v220, 0xffff0000, v220
	v_pk_add_f32 v[230:231], v[230:231], v[220:221]
	v_lshlrev_b32_e32 v49, 16, v223
	v_lshlrev_b32_e32 v48, 16, v222
	v_pk_add_f32 v[228:229], v[228:229], v[48:49]
	v_and_b32_e32 v223, 0xffff0000, v223
	v_and_b32_e32 v222, 0xffff0000, v222
	v_pk_add_f32 v[230:231], v[230:231], v[222:223]
	s_waitcnt lgkmcnt(15)
	v_lshlrev_b32_e32 v49, 16, v225
	v_lshlrev_b32_e32 v48, 16, v224
	global_load_dwordx4 v[68:71], v233, s[34:35]
	v_pk_add_f32 v[228:229], v[228:229], v[48:49]
	v_and_b32_e32 v225, 0xffff0000, v225
	v_and_b32_e32 v224, 0xffff0000, v224
	v_pk_add_f32 v[230:231], v[230:231], v[224:225]
	v_lshlrev_b32_e32 v49, 16, v227
	v_lshlrev_b32_e32 v48, 16, v226
	v_pk_add_f32 v[228:229], v[228:229], v[48:49]
	v_and_b32_e32 v227, 0xffff0000, v227
	v_and_b32_e32 v226, 0xffff0000, v226
	v_pk_add_f32 v[230:231], v[230:231], v[226:227]
	global_load_dwordx4 v[72:75], v251, s[36:37]
	v_cvt_pk_bf16_f32 v228, v228, v229
	v_cvt_pk_bf16_f32 v230, v230, v231
	global_store_dword v249, v228, s[38:39]
	global_store_dword v250, v230, s[38:39]
	s_add_u32 s38, s38, s55
	s_addc_u32 s39, s39, s56
	s_add_u32 s32, s32, s53
	s_addc_u32 s33, s33, s56
	s_add_u32 s34, s34, s53
	s_addc_u32 s35, s35, s56
	s_add_u32 s36, s36, s54
	s_addc_u32 s37, s37, s56
	s_waitcnt lgkmcnt(0)
	s_barrier
; __device__ __forceinline__ void phase_scan(const Args& a, unsigned char* smem, int tid, int lane, int wave) {
;     ...
;             if (gc < 512) {
;                 u32x4 s0, s1;
;                 s0.x = pk2(S[0], S[1]); s0.y = pk2(S[2], S[3]); s0.z = pk2(S[4], S[5]); s0.w = pk2(S[6], S[7]);
;                 s1.x = pk2(S[8], S[9]); s1.y = pk2(S[10], S[11]); s1.z = pk2(S[12], S[13]); s1.w = pk2(S[14], S[15]);
;                 const bf16x8 sb0 = __builtin_bit_cast(bf16x8, s0), sb1 = __builtin_bit_cast(bf16x8, s1);
;                 f32x16 o0, o1;
; #pragma unroll
;                 for (int i = 0; i < 16; ++i) { o0[i] = 0.f; o1[i] = 0.f; }
;                 o0 = mfma32(qeA[0], sb0, o0); o0 = mfma32(qeA[1], sb1, o0);
;                 o1 = mfma32(qeA[2], sb0, o1); o1 = mfma32(qeA[3], sb1, o1);
;                 const int w3 = wave & 3;
;                 const bf16x8 vs = w3 == 0 ? vB[0] : (w3 == 1 ? vB[1] : (w3 == 2 ? vB[2] : vB[3]));
;                 if (wave < 4) o0 = mfma32(atA, vs, o0); else o1 = mfma32(atA, vs, o1);
;                 unsigned* rb = red + (size_t)(rbuf * 8 + wave) * 1024 + lane; unsigned* rbx = red + (size_t)(rbuf * 8 + wave) * 1024 + (lane ^ 32);
; #pragma unroll
;                 for (int i = 0; i < 8; ++i) { unsigned* w_ = (i & 1) ? rbx : rb; w_[i * 64] = pk2(o0[2 * i], o0[2 * i + 1]); w_[512 + i * 64] = pk2(o1[2 * i], o1[2 * i + 1]); }
;             }
;             SCAN_GSTORE(nbuf, gcur);
;             __syncthreads();
;             if (gc < 512) {
;                 const int tp = tid >> 4, dv2 = (tid & 15) * 2, t = tp * 2, mt = t >> 5, tl = t & 31, pi = 2 * (tl >> 3) + ((tl & 3) >> 1), ln = ((tl >> 2) & 1) * 32 + dv2;
;                 const unsigned* rp = red + (size_t)rbuf * 8192 + (mt * 8 + pi) * 64 + (ln ^ ((pi & 1) << 5));
;                 float a0 = 0.f, a1 = 0.f, b0 = 0.f, b1 = 0.f;
; #pragma unroll
;                 for (int w = 0; w < 8; ++w) { const u32x2 v = *(const u32x2*)(rp + w * 1024); a0 += bflo(v.x); b0 += bfhi(v.x); a1 += bflo(v.y); b1 += bfhi(v.y); }
;                 bf16_t* op = O + (row0 + t) * 2048 + h * 512 + sl * 32 + dv2;
;                 *(unsigned*)op = pk2(a0, a1); *(unsigned*)(op + 2048) = pk2(b0, b1);
;             }
;             f32x4 ndl[4]; bf16x8 nvB[4];
;             SCAN_LREAD(nbuf, nvB, ndl);
; #pragma unroll
;             for (int i = 0; i < 16; ++i) S[i] *= dl[i >> 2][i & 3];
; #pragma unroll
	s_waitcnt vmcnt(12)
	ds_write_b128 v240, v[208:211]
	global_load_dwordx4 v[208:211], v[194:195], off
	v_lshl_add_u64 v[194:195], v[194:195], 0, v[254:255]
	v_cvt_pk_bf16_f32 v48, v0, v1
	v_cvt_pk_bf16_f32 v49, v2, v3
	v_cvt_pk_bf16_f32 v50, v4, v5
	v_cvt_pk_bf16_f32 v51, v6, v7
	v_cvt_pk_bf16_f32 v52, v8, v9
	v_cvt_pk_bf16_f32 v53, v10, v11
	v_cvt_pk_bf16_f32 v54, v12, v13
	v_cvt_pk_bf16_f32 v55, v14, v15
	v_mfma_f32_32x32x16_bf16 v[16:31], v[92:95], v[48:51], 0
	v_pk_mul_f32 v[0:1], v[178:179], v[0:1]
	v_pk_mul_f32 v[2:3], v[180:181], v[2:3]
	v_pk_mul_f32 v[4:5], v[182:183], v[4:5]
	v_mfma_f32_32x32x16_bf16 v[32:47], v[100:103], v[48:51], 0
	v_pk_mul_f32 v[6:7], v[184:185], v[6:7]
	v_pk_mul_f32 v[8:9], v[186:187], v[8:9]
	v_pk_mul_f32 v[10:11], v[188:189], v[10:11]
	v_mfma_f32_32x32x16_bf16 v[16:31], v[96:99], v[52:55], v[16:31]
	v_pk_mul_f32 v[12:13], v[190:191], v[12:13]
	v_pk_mul_f32 v[14:15], v[192:193], v[14:15]
	v_mfma_f32_32x32x16_bf16 v[32:47], v[104:107], v[52:55], v[32:47]
	v_mfma_f32_32x32x16_bf16 v[16:31], v[108:111], v[200:203], v[16:31]
	v_mfma_f32_32x32x16_bf16 v[0:15], v[112:115], v[144:147], v[0:15]
	v_mfma_f32_32x32x16_bf16 v[0:15], v[116:119], v[148:151], v[0:15]
	v_mfma_f32_32x32x16_bf16 v[0:15], v[120:123], v[152:155], v[0:15]
	v_mfma_f32_32x32x16_bf16 v[0:15], v[124:127], v[156:159], v[0:15]
	ds_read2st64_b64 v[212:215], v245 offset0:0 offset1:8
	ds_read2st64_b64 v[216:219], v245 offset0:16 offset1:24
	ds_read2st64_b64 v[220:223], v245 offset0:32 offset1:40
	ds_read2st64_b64 v[224:227], v245 offset0:48 offset1:56
	ds_read_b128 v[128:131], v246 offset:0
	global_load_dwordx4 v[112:115], v235, s[32:33]
	ds_read_b128 v[132:135], v246 offset:1024
	ds_read_b128 v[136:139], v246 offset:2048
	ds_read_b128 v[140:143], v246 offset:3072
	ds_read_b128 v[196:199], v248 offset:0
	ds_read_b128 v[162:165], v247 offset:0
	ds_read_b128 v[166:169], v247 offset:32
	ds_read_b128 v[170:173], v247 offset:64
	ds_read_b128 v[174:177], v247 offset:96
	v_cvt_pk_bf16_f32 v16, v16, v17
	v_cvt_pk_bf16_f32 v18, v18, v19
	global_load_dwordx4 v[116:119], v235, s[32:33] offset:1024
	v_cvt_pk_bf16_f32 v20, v20, v21
	v_cvt_pk_bf16_f32 v22, v22, v23
	v_cvt_pk_bf16_f32 v24, v24, v25
	v_cvt_pk_bf16_f32 v26, v26, v27
	v_cvt_pk_bf16_f32 v28, v28, v29
	v_cvt_pk_bf16_f32 v30, v30, v31
	ds_write2st64_b32 v241, v16, v20 offset0:128 offset1:130
	ds_write2st64_b32 v242, v18, v22 offset0:129 offset1:131
	ds_write2st64_b32 v241, v24, v28 offset0:132 offset1:134
	ds_write2st64_b32 v242, v26, v30 offset0:133 offset1:135
	v_cvt_pk_bf16_f32 v32, v32, v33
	global_load_dwordx4 v[120:123], v235, s[32:33] offset:2048
	v_cvt_pk_bf16_f32 v34, v34, v35
	v_cvt_pk_bf16_f32 v36, v36, v37
	v_cvt_pk_bf16_f32 v38, v38, v39
	v_cvt_pk_bf16_f32 v40, v40, v41
	v_cvt_pk_bf16_f32 v42, v42, v43
	v_cvt_pk_bf16_f32 v44, v44, v45
	v_cvt_pk_bf16_f32 v46, v46, v47
	ds_write2st64_b32 v243, v32, v36 offset0:128 offset1:130
	ds_write2st64_b32 v244, v34, v38 offset0:129 offset1:131
	ds_write2st64_b32 v243, v40, v44 offset0:132 offset1:134
	global_load_dwordx4 v[124:127], v235, s[32:33] offset:3072
	ds_write2st64_b32 v244, v42, v46 offset0:133 offset1:135
	s_waitcnt lgkmcnt(15)
	v_lshlrev_b32_e32 v229, 16, v213
	v_lshlrev_b32_e32 v228, 16, v212
	v_pk_add_f32 v[228:229], v[228:229], 0 op_sel_hi:[1,0]
	v_and_b32_e32 v231, 0xffff0000, v213
	v_and_b32_e32 v230, 0xffff0000, v212
	v_pk_add_f32 v[230:231], v[230:231], 0 op_sel_hi:[1,0]
	v_lshlrev_b32_e32 v49, 16, v215
	v_lshlrev_b32_e32 v48, 16, v214
	v_pk_add_f32 v[228:229], v[228:229], v[48:49]
	global_load_dwordx4 v[92:95], v232, s[34:35] offset:-4096
	v_and_b32_e32 v215, 0xffff0000, v215
	v_and_b32_e32 v214, 0xffff0000, v214
	v_pk_add_f32 v[230:231], v[230:231], v[214:215]
	s_waitcnt lgkmcnt(15)
	v_lshlrev_b32_e32 v49, 16, v217
	v_lshlrev_b32_e32 v48, 16, v216
	v_pk_add_f32 v[228:229], v[228:229], v[48:49]
	v_and_b32_e32 v217, 0xffff0000, v217
	v_and_b32_e32 v216, 0xffff0000, v216
	v_pk_add_f32 v[230:231], v[230:231], v[216:217]
	v_lshlrev_b32_e32 v49, 16, v219
	global_load_dwordx4 v[96:99], v232, s[34:35]
	v_lshlrev_b32_e32 v48, 16, v218
	v_pk_add_f32 v[228:229], v[228:229], v[48:49]
	v_and_b32_e32 v219, 0xffff0000, v219
	v_and_b32_e32 v218, 0xffff0000, v218
	v_pk_add_f32 v[230:231], v[230:231], v[218:219]
	s_waitcnt lgkmcnt(15)
	v_lshlrev_b32_e32 v49, 16, v221
	v_lshlrev_b32_e32 v48, 16, v220
	v_pk_add_f32 v[228:229], v[228:229], v[48:49]
	v_and_b32_e32 v221, 0xffff0000, v221
	global_load_dwordx4 v[100:103], v233, s[34:35] offset:-4096
	v_and_b32_e32 v220, 0xffff0000, v220
	v_pk_add_f32 v[230:231], v[230:231], v[220:221]
	v_lshlrev_b32_e32 v49, 16, v223
	v_lshlrev_b32_e32 v48, 16, v222
	v_pk_add_f32 v[228:229], v[228:229], v[48:49]
	v_and_b32_e32 v223, 0xffff0000, v223
	v_and_b32_e32 v222, 0xffff0000, v222
	v_pk_add_f32 v[230:231], v[230:231], v[222:223]
	s_waitcnt lgkmcnt(15)
	v_lshlrev_b32_e32 v49, 16, v225
	v_lshlrev_b32_e32 v48, 16, v224
	global_load_dwordx4 v[104:107], v233, s[34:35]
	v_pk_add_f32 v[228:229], v[228:229], v[48:49]
	v_and_b32_e32 v225, 0xffff0000, v225
	v_and_b32_e32 v224, 0xffff0000, v224
	v_pk_add_f32 v[230:231], v[230:231], v[224:225]
	v_lshlrev_b32_e32 v49, 16, v227
	v_lshlrev_b32_e32 v48, 16, v226
	v_pk_add_f32 v[228:229], v[228:229], v[48:49]
	v_and_b32_e32 v227, 0xffff0000, v227
	v_and_b32_e32 v226, 0xffff0000, v226
	v_pk_add_f32 v[230:231], v[230:231], v[226:227]
	global_load_dwordx4 v[108:111], v251, s[36:37]
	v_cvt_pk_bf16_f32 v228, v228, v229
	v_cvt_pk_bf16_f32 v230, v230, v231
	global_store_dword v249, v228, s[38:39]
	global_store_dword v250, v230, s[38:39]
	s_add_u32 s38, s38, s55
	s_addc_u32 s39, s39, s56
	s_add_u32 s32, s32, s53
	s_addc_u32 s33, s33, s56
	s_add_u32 s34, s34, s53
	s_addc_u32 s35, s35, s56
	s_add_u32 s36, s36, s54
	s_addc_u32 s37, s37, s56
	s_waitcnt lgkmcnt(0)
	s_barrier
	s_mov_b32 s30, 4
; __device__ __forceinline__ void phase_scan(const Args& a, unsigned char* smem, int tid, int lane, int wave) {
;     ...
;             if (gc < 512) {
;                 u32x4 s0, s1;
;                 s0.x = pk2(S[0], S[1]); s0.y = pk2(S[2], S[3]); s0.z = pk2(S[4], S[5]); s0.w = pk2(S[6], S[7]);
;                 s1.x = pk2(S[8], S[9]); s1.y = pk2(S[10], S[11]); s1.z = pk2(S[12], S[13]); s1.w = pk2(S[14], S[15]);
;                 const bf16x8 sb0 = __builtin_bit_cast(bf16x8, s0), sb1 = __builtin_bit_cast(bf16x8, s1);
;                 f32x16 o0, o1;
; #pragma unroll
;                 for (int i = 0; i < 16; ++i) { o0[i] = 0.f; o1[i] = 0.f; }
;                 o0 = mfma32(qeA[0], sb0, o0); o0 = mfma32(qeA[1], sb1, o0);
;                 o1 = mfma32(qeA[2], sb0, o1); o1 = mfma32(qeA[3], sb1, o1);
;                 const int w3 = wave & 3;
;                 const bf16x8 vs = w3 == 0 ? vB[0] : (w3 == 1 ? vB[1] : (w3 == 2 ? vB[2] : vB[3]));
;                 if (wave < 4) o0 = mfma32(atA, vs, o0); else o1 = mfma32(atA, vs, o1);
;                 unsigned* rb = red + (size_t)(rbuf * 8 + wave) * 1024 + lane; unsigned* rbx = red + (size_t)(rbuf * 8 + wave) * 1024 + (lane ^ 32);
; #pragma unroll
;                 for (int i = 0; i < 8; ++i) { unsigned* w_ = (i & 1) ? rbx : rb; w_[i * 64] = pk2(o0[2 * i], o0[2 * i + 1]); w_[512 + i * 64] = pk2(o1[2 * i], o1[2 * i + 1]); }
;             }
;             SCAN_GSTORE(nbuf, gcur);
;             __syncthreads();
;             if (gc < 512) {
;                 const int tp = tid >> 4, dv2 = (tid & 15) * 2, t = tp * 2, mt = t >> 5, tl = t & 31, pi = 2 * (tl >> 3) + ((tl & 3) >> 1), ln = ((tl >> 2) & 1) * 32 + dv2;
;                 const unsigned* rp = red + (size_t)rbuf * 8192 + (mt * 8 + pi) * 64 + (ln ^ ((pi & 1) << 5));
;                 float a0 = 0.f, a1 = 0.f, b0 = 0.f, b1 = 0.f;
; #pragma unroll
;                 for (int w = 0; w < 8; ++w) { const u32x2 v = *(const u32x2*)(rp + w * 1024); a0 += bflo(v.x); b0 += bfhi(v.x); a1 += bflo(v.y); b1 += bfhi(v.y); }
;                 bf16_t* op = O + (row0 + t) * 2048 + h * 512 + sl * 32 + dv2;
;                 *(unsigned*)op = pk2(a0, a1); *(unsigned*)(op + 2048) = pk2(b0, b1);
;             }
;             f32x4 ndl[4]; bf16x8 nvB[4];
;             SCAN_LREAD(nbuf, nvB, ndl);
; #pragma unroll
;             for (int i = 0; i < 16; ++i) S[i] *= dl[i >> 2][i & 3];
; #pragma unroll
.Lscan_loopA:
	s_waitcnt vmcnt(12)
	ds_write_b128 v239, v[204:207]
	global_load_dwordx4 v[204:207], v[194:195], off
	v_lshl_add_u64 v[194:195], v[194:195], 0, v[254:255]
	v_cvt_pk_bf16_f32 v48, v0, v1
	v_cvt_pk_bf16_f32 v49, v2, v3
	v_cvt_pk_bf16_f32 v50, v4, v5
	v_cvt_pk_bf16_f32 v51, v6, v7
	v_cvt_pk_bf16_f32 v52, v8, v9
	v_cvt_pk_bf16_f32 v53, v10, v11
	v_cvt_pk_bf16_f32 v54, v12, v13
	v_cvt_pk_bf16_f32 v55, v14, v15
	v_mfma_f32_32x32x16_bf16 v[16:31], v[56:59], v[48:51], 0
	v_pk_mul_f32 v[0:1], v[162:163], v[0:1]
	v_pk_mul_f32 v[2:3], v[164:165], v[2:3]
	v_pk_mul_f32 v[4:5], v[166:167], v[4:5]
	v_mfma_f32_32x32x16_bf16 v[32:47], v[64:67], v[48:51], 0
	v_pk_mul_f32 v[6:7], v[168:169], v[6:7]
	v_pk_mul_f32 v[8:9], v[170:171], v[8:9]
	v_pk_mul_f32 v[10:11], v[172:173], v[10:11]
	v_mfma_f32_32x32x16_bf16 v[16:31], v[60:63], v[52:55], v[16:31]
	v_pk_mul_f32 v[12:13], v[174:175], v[12:13]
	v_pk_mul_f32 v[14:15], v[176:177], v[14:15]
	v_mfma_f32_32x32x16_bf16 v[32:47], v[68:71], v[52:55], v[32:47]
	v_mfma_f32_32x32x16_bf16 v[16:31], v[72:75], v[196:199], v[16:31]
	v_mfma_f32_32x32x16_bf16 v[0:15], v[76:79], v[128:131], v[0:15]
	v_mfma_f32_32x32x16_bf16 v[0:15], v[80:83], v[132:135], v[0:15]
	v_mfma_f32_32x32x16_bf16 v[0:15], v[84:87], v[136:139], v[0:15]
	v_mfma_f32_32x32x16_bf16 v[0:15], v[88:91], v[140:143], v[0:15]
	ds_read2st64_b64 v[212:215], v245 offset0:64 offset1:72
	ds_read2st64_b64 v[216:219], v245 offset0:80 offset1:88
	ds_read2st64_b64 v[220:223], v245 offset0:96 offset1:104
	ds_read2st64_b64 v[224:227], v245 offset0:112 offset1:120
	ds_read_b128 v[144:147], v246 offset:4096
	global_load_dwordx4 v[76:79], v235, s[32:33]
	ds_read_b128 v[148:151], v246 offset:5120
	ds_read_b128 v[152:155], v246 offset:6144
	ds_read_b128 v[156:159], v246 offset:7168
	ds_read_b128 v[200:203], v248 offset:4096
	ds_read_b128 v[178:181], v247 offset:1024
	ds_read_b128 v[182:185], v247 offset:1056
	ds_read_b128 v[186:189], v247 offset:1088
	ds_read_b128 v[190:193], v247 offset:1120
	v_cvt_pk_bf16_f32 v16, v16, v17
	v_cvt_pk_bf16_f32 v18, v18, v19
	global_load_dwordx4 v[80:83], v235, s[32:33] offset:1024
	v_cvt_pk_bf16_f32 v20, v20, v21
	v_cvt_pk_bf16_f32 v22, v22, v23
	v_cvt_pk_bf16_f32 v24, v24, v25
	v_cvt_pk_bf16_f32 v26, v26, v27
	v_cvt_pk_bf16_f32 v28, v28, v29
	v_cvt_pk_bf16_f32 v30, v30, v31
	ds_write2st64_b32 v241, v16, v20 offset0:0 offset1:2
	ds_write2st64_b32 v242, v18, v22 offset0:1 offset1:3
	ds_write2st64_b32 v241, v24, v28 offset0:4 offset1:6
	ds_write2st64_b32 v242, v26, v30 offset0:5 offset1:7
	v_cvt_pk_bf16_f32 v32, v32, v33
	global_load_dwordx4 v[84:87], v235, s[32:33] offset:2048
	v_cvt_pk_bf16_f32 v34, v34, v35
	v_cvt_pk_bf16_f32 v36, v36, v37
	v_cvt_pk_bf16_f32 v38, v38, v39
	v_cvt_pk_bf16_f32 v40, v40, v41
	v_cvt_pk_bf16_f32 v42, v42, v43
	v_cvt_pk_bf16_f32 v44, v44, v45
	v_cvt_pk_bf16_f32 v46, v46, v47
	ds_write2st64_b32 v243, v32, v36 offset0:0 offset1:2
	ds_write2st64_b32 v244, v34, v38 offset0:1 offset1:3
	ds_write2st64_b32 v243, v40, v44 offset0:4 offset1:6
	global_load_dwordx4 v[88:91], v235, s[32:33] offset:3072
	ds_write2st64_b32 v244, v42, v46 offset0:5 offset1:7
	s_waitcnt lgkmcnt(15)
	v_lshlrev_b32_e32 v229, 16, v213
	v_lshlrev_b32_e32 v228, 16, v212
	v_pk_add_f32 v[228:229], v[228:229], 0 op_sel_hi:[1,0]
	v_and_b32_e32 v231, 0xffff0000, v213
	v_and_b32_e32 v230, 0xffff0000, v212
	v_pk_add_f32 v[230:231], v[230:231], 0 op_sel_hi:[1,0]
	v_lshlrev_b32_e32 v49, 16, v215
	v_lshlrev_b32_e32 v48, 16, v214
	v_pk_add_f32 v[228:229], v[228:229], v[48:49]
	global_load_dwordx4 v[56:59], v232, s[34:35] offset:-4096
	v_and_b32_e32 v215, 0xffff0000, v215
	v_and_b32_e32 v214, 0xffff0000, v214
	v_pk_add_f32 v[230:231], v[230:231], v[214:215]
	s_waitcnt lgkmcnt(15)
	v_lshlrev_b32_e32 v49, 16, v217
	v_lshlrev_b32_e32 v48, 16, v216
	v_pk_add_f32 v[228:229], v[228:229], v[48:49]
	v_and_b32_e32 v217, 0xffff0000, v217
	v_and_b32_e32 v216, 0xffff0000, v216
	v_pk_add_f32 v[230:231], v[230:231], v[216:217]
	v_lshlrev_b32_e32 v49, 16, v219
	global_load_dwordx4 v[60:63], v232, s[34:35]
	v_lshlrev_b32_e32 v48, 16, v218
	v_pk_add_f32 v[228:229], v[228:229], v[48:49]
	v_and_b32_e32 v219, 0xffff0000, v219
	v_and_b32_e32 v218, 0xffff0000, v218
	v_pk_add_f32 v[230:231], v[230:231], v[218:219]
	s_waitcnt lgkmcnt(15)
	v_lshlrev_b32_e32 v49, 16, v221
	v_lshlrev_b32_e32 v48, 16, v220
	v_pk_add_f32 v[228:229], v[228:229], v[48:49]
	v_and_b32_e32 v221, 0xffff0000, v221
	global_load_dwordx4 v[64:67], v233, s[34:35] offset:-4096
	v_and_b32_e32 v220, 0xffff0000, v220
	v_pk_add_f32 v[230:231], v[230:231], v[220:221]
	v_lshlrev_b32_e32 v49, 16, v223
	v_lshlrev_b32_e32 v48, 16, v222
	v_pk_add_f32 v[228:229], v[228:229], v[48:49]
	v_and_b32_e32 v223, 0xffff0000, v223
	v_and_b32_e32 v222, 0xffff0000, v222
	v_pk_add_f32 v[230:231], v[230:231], v[222:223]
	s_waitcnt lgkmcnt(15)
	v_lshlrev_b32_e32 v49, 16, v225
	v_lshlrev_b32_e32 v48, 16, v224
	global_load_dwordx4 v[68:71], v233, s[34:35]
	v_pk_add_f32 v[228:229], v[228:229], v[48:49]
	v_and_b32_e32 v225, 0xffff0000, v225
	v_and_b32_e32 v224, 0xffff0000, v224
	v_pk_add_f32 v[230:231], v[230:231], v[224:225]
	v_lshlrev_b32_e32 v49, 16, v227
	v_lshlrev_b32_e32 v48, 16, v226
	v_pk_add_f32 v[228:229], v[228:229], v[48:49]
	v_and_b32_e32 v227, 0xffff0000, v227
	v_and_b32_e32 v226, 0xffff0000, v226
	v_pk_add_f32 v[230:231], v[230:231], v[226:227]
	global_load_dwordx4 v[72:75], v251, s[36:37]
	v_cvt_pk_bf16_f32 v228, v228, v229
	v_cvt_pk_bf16_f32 v230, v230, v231
	global_store_dword v249, v228, s[38:39]
	global_store_dword v250, v230, s[38:39]
	s_add_u32 s38, s38, s55
	s_addc_u32 s39, s39, s56
	s_add_u32 s32, s32, s53
	s_addc_u32 s33, s33, s56
	s_add_u32 s34, s34, s53
	s_addc_u32 s35, s35, s56
	s_add_u32 s36, s36, s54
	s_addc_u32 s37, s37, s56
	s_waitcnt lgkmcnt(0)
	s_barrier
; __device__ __forceinline__ void phase_scan(const Args& a, unsigned char* smem, int tid, int lane, int wave) {
;     ...
;             if (gc < 512) {
;                 u32x4 s0, s1;
;                 s0.x = pk2(S[0], S[1]); s0.y = pk2(S[2], S[3]); s0.z = pk2(S[4], S[5]); s0.w = pk2(S[6], S[7]);
;                 s1.x = pk2(S[8], S[9]); s1.y = pk2(S[10], S[11]); s1.z = pk2(S[12], S[13]); s1.w = pk2(S[14], S[15]);
;                 const bf16x8 sb0 = __builtin_bit_cast(bf16x8, s0), sb1 = __builtin_bit_cast(bf16x8, s1);
;                 f32x16 o0, o1;
; #pragma unroll
;                 for (int i = 0; i < 16; ++i) { o0[i] = 0.f; o1[i] = 0.f; }
;                 o0 = mfma32(qeA[0], sb0, o0); o0 = mfma32(qeA[1], sb1, o0);
;                 o1 = mfma32(qeA[2], sb0, o1); o1 = mfma32(qeA[3], sb1, o1);
;                 const int w3 = wave & 3;
;                 const bf16x8 vs = w3 == 0 ? vB[0] : (w3 == 1 ? vB[1] : (w3 == 2 ? vB[2] : vB[3]));
;                 if (wave < 4) o0 = mfma32(atA, vs, o0); else o1 = mfma32(atA, vs, o1);
;                 unsigned* rb = red + (size_t)(rbuf * 8 + wave) * 1024 + lane; unsigned* rbx = red + (size_t)(rbuf * 8 + wave) * 1024 + (lane ^ 32);
; #pragma unroll
;                 for (int i = 0; i < 8; ++i) { unsigned* w_ = (i & 1) ? rbx : rb; w_[i * 64] = pk2(o0[2 * i], o0[2 * i + 1]); w_[512 + i * 64] = pk2(o1[2 * i], o1[2 * i + 1]); }
;             }
;             SCAN_GSTORE(nbuf, gcur);
;             __syncthreads();
;             if (gc < 512) {
;                 const int tp = tid >> 4, dv2 = (tid & 15) * 2, t = tp * 2, mt = t >> 5, tl = t & 31, pi = 2 * (tl >> 3) + ((tl & 3) >> 1), ln = ((tl >> 2) & 1) * 32 + dv2;
;                 const unsigned* rp = red + (size_t)rbuf * 8192 + (mt * 8 + pi) * 64 + (ln ^ ((pi & 1) << 5));
;                 float a0 = 0.f, a1 = 0.f, b0 = 0.f, b1 = 0.f;
; #pragma unroll
;                 for (int w = 0; w < 8; ++w) { const u32x2 v = *(const u32x2*)(rp + w * 1024); a0 += bflo(v.x); b0 += bfhi(v.x); a1 += bflo(v.y); b1 += bfhi(v.y); }
;                 bf16_t* op = O + (row0 + t) * 2048 + h * 512 + sl * 32 + dv2;
;                 *(unsigned*)op = pk2(a0, a1); *(unsigned*)(op + 2048) = pk2(b0, b1);
;             }
;             f32x4 ndl[4]; bf16x8 nvB[4];
;             SCAN_LREAD(nbuf, nvB, ndl);
; #pragma unroll
;             for (int i = 0; i < 16; ++i) S[i] *= dl[i >> 2][i & 3];
; #pragma unroll
	s_waitcnt vmcnt(12)
	ds_write_b128 v240, v[208:211]
	global_load_dwordx4 v[208:211], v[194:195], off
	v_lshl_add_u64 v[194:195], v[194:195], 0, v[254:255]
	v_cvt_pk_bf16_f32 v48, v0, v1
	v_cvt_pk_bf16_f32 v49, v2, v3
	v_cvt_pk_bf16_f32 v50, v4, v5
	v_cvt_pk_bf16_f32 v51, v6, v7
	v_cvt_pk_bf16_f32 v52, v8, v9
	v_cvt_pk_bf16_f32 v53, v10, v11
	v_cvt_pk_bf16_f32 v54, v12, v13
	v_cvt_pk_bf16_f32 v55, v14, v15
	v_mfma_f32_32x32x16_bf16 v[16:31], v[92:95], v[48:51], 0
	v_pk_mul_f32 v[0:1], v[178:179], v[0:1]
	v_pk_mul_f32 v[2:3], v[180:181], v[2:3]
	v_pk_mul_f32 v[4:5], v[182:183], v[4:5]
	v_mfma_f32_32x32x16_bf16 v[32:47], v[100:103], v[48:51], 0
	v_pk_mul_f32 v[6:7], v[184:185], v[6:7]
	v_pk_mul_f32 v[8:9], v[186:187], v[8:9]
	v_pk_mul_f32 v[10:11], v[188:189], v[10:11]
	v_mfma_f32_32x32x16_bf16 v[16:31], v[96:99], v[52:55], v[16:31]
	v_pk_mul_f32 v[12:13], v[190:191], v[12:13]
	v_pk_mul_f32 v[14:15], v[192:193], v[14:15]
	v_mfma_f32_32x32x16_bf16 v[32:47], v[104:107], v[52:55], v[32:47]
	v_mfma_f32_32x32x16_bf16 v[16:31], v[108:111], v[200:203], v[16:31]
	v_mfma_f32_32x32x16_bf16 v[0:15], v[112:115], v[144:147], v[0:15]
	v_mfma_f32_32x32x16_bf16 v[0:15], v[116:119], v[148:151], v[0:15]
	v_mfma_f32_32x32x16_bf16 v[0:15], v[120:123], v[152:155], v[0:15]
	v_mfma_f32_32x32x16_bf16 v[0:15], v[124:127], v[156:159], v[0:15]
	ds_read2st64_b64 v[212:215], v245 offset0:0 offset1:8
	ds_read2st64_b64 v[216:219], v245 offset0:16 offset1:24
	ds_read2st64_b64 v[220:223], v245 offset0:32 offset1:40
	ds_read2st64_b64 v[224:227], v245 offset0:48 offset1:56
	ds_read_b128 v[128:131], v246 offset:0
	global_load_dwordx4 v[112:115], v235, s[32:33]
	ds_read_b128 v[132:135], v246 offset:1024
	ds_read_b128 v[136:139], v246 offset:2048
	ds_read_b128 v[140:143], v246 offset:3072
	ds_read_b128 v[196:199], v248 offset:0
	ds_read_b128 v[162:165], v247 offset:0
	ds_read_b128 v[166:169], v247 offset:32
	ds_read_b128 v[170:173], v247 offset:64
	ds_read_b128 v[174:177], v247 offset:96
	v_cvt_pk_bf16_f32 v16, v16, v17
	v_cvt_pk_bf16_f32 v18, v18, v19
	global_load_dwordx4 v[116:119], v235, s[32:33] offset:1024
	v_cvt_pk_bf16_f32 v20, v20, v21
	v_cvt_pk_bf16_f32 v22, v22, v23
	v_cvt_pk_bf16_f32 v24, v24, v25
	v_cvt_pk_bf16_f32 v26, v26, v27
	v_cvt_pk_bf16_f32 v28, v28, v29
	v_cvt_pk_bf16_f32 v30, v30, v31
	ds_write2st64_b32 v241, v16, v20 offset0:128 offset1:130
	ds_write2st64_b32 v242, v18, v22 offset0:129 offset1:131
	ds_write2st64_b32 v241, v24, v28 offset0:132 offset1:134
	ds_write2st64_b32 v242, v26, v30 offset0:133 offset1:135
	v_cvt_pk_bf16_f32 v32, v32, v33
	global_load_dwordx4 v[120:123], v235, s[32:33] offset:2048
	v_cvt_pk_bf16_f32 v34, v34, v35
	v_cvt_pk_bf16_f32 v36, v36, v37
	v_cvt_pk_bf16_f32 v38, v38, v39
	v_cvt_pk_bf16_f32 v40, v40, v41
	v_cvt_pk_bf16_f32 v42, v42, v43
	v_cvt_pk_bf16_f32 v44, v44, v45
	v_cvt_pk_bf16_f32 v46, v46, v47
	ds_write2st64_b32 v243, v32, v36 offset0:128 offset1:130
	ds_write2st64_b32 v244, v34, v38 offset0:129 offset1:131
	ds_write2st64_b32 v243, v40, v44 offset0:132 offset1:134
	global_load_dwordx4 v[124:127], v235, s[32:33] offset:3072
	ds_write2st64_b32 v244, v42, v46 offset0:133 offset1:135
	s_waitcnt lgkmcnt(15)
	v_lshlrev_b32_e32 v229, 16, v213
	v_lshlrev_b32_e32 v228, 16, v212
	v_pk_add_f32 v[228:229], v[228:229], 0 op_sel_hi:[1,0]
	v_and_b32_e32 v231, 0xffff0000, v213
	v_and_b32_e32 v230, 0xffff0000, v212
	v_pk_add_f32 v[230:231], v[230:231], 0 op_sel_hi:[1,0]
	v_lshlrev_b32_e32 v49, 16, v215
	v_lshlrev_b32_e32 v48, 16, v214
	v_pk_add_f32 v[228:229], v[228:229], v[48:49]
	global_load_dwordx4 v[92:95], v232, s[34:35] offset:-4096
	v_and_b32_e32 v215, 0xffff0000, v215
	v_and_b32_e32 v214, 0xffff0000, v214
	v_pk_add_f32 v[230:231], v[230:231], v[214:215]
	s_waitcnt lgkmcnt(15)
	v_lshlrev_b32_e32 v49, 16, v217
	v_lshlrev_b32_e32 v48, 16, v216
	v_pk_add_f32 v[228:229], v[228:229], v[48:49]
	v_and_b32_e32 v217, 0xffff0000, v217
	v_and_b32_e32 v216, 0xffff0000, v216
	v_pk_add_f32 v[230:231], v[230:231], v[216:217]
	v_lshlrev_b32_e32 v49, 16, v219
	global_load_dwordx4 v[96:99], v232, s[34:35]
	v_lshlrev_b32_e32 v48, 16, v218
	v_pk_add_f32 v[228:229], v[228:229], v[48:49]
	v_and_b32_e32 v219, 0xffff0000, v219
	v_and_b32_e32 v218, 0xffff0000, v218
	v_pk_add_f32 v[230:231], v[230:231], v[218:219]
	s_waitcnt lgkmcnt(15)
	v_lshlrev_b32_e32 v49, 16, v221
	v_lshlrev_b32_e32 v48, 16, v220
	v_pk_add_f32 v[228:229], v[228:229], v[48:49]
	v_and_b32_e32 v221, 0xffff0000, v221
	global_load_dwordx4 v[100:103], v233, s[34:35] offset:-4096
	v_and_b32_e32 v220, 0xffff0000, v220
	v_pk_add_f32 v[230:231], v[230:231], v[220:221]
	v_lshlrev_b32_e32 v49, 16, v223
	v_lshlrev_b32_e32 v48, 16, v222
	v_pk_add_f32 v[228:229], v[228:229], v[48:49]
	v_and_b32_e32 v223, 0xffff0000, v223
	v_and_b32_e32 v222, 0xffff0000, v222
	v_pk_add_f32 v[230:231], v[230:231], v[222:223]
	s_waitcnt lgkmcnt(15)
	v_lshlrev_b32_e32 v49, 16, v225
	v_lshlrev_b32_e32 v48, 16, v224
	global_load_dwordx4 v[104:107], v233, s[34:35]
	v_pk_add_f32 v[228:229], v[228:229], v[48:49]
	v_and_b32_e32 v225, 0xffff0000, v225
	v_and_b32_e32 v224, 0xffff0000, v224
	v_pk_add_f32 v[230:231], v[230:231], v[224:225]
	v_lshlrev_b32_e32 v49, 16, v227
	v_lshlrev_b32_e32 v48, 16, v226
	v_pk_add_f32 v[228:229], v[228:229], v[48:49]
	v_and_b32_e32 v227, 0xffff0000, v227
	v_and_b32_e32 v226, 0xffff0000, v226
	v_pk_add_f32 v[230:231], v[230:231], v[226:227]
	global_load_dwordx4 v[108:111], v251, s[36:37]
	v_cvt_pk_bf16_f32 v228, v228, v229
	v_cvt_pk_bf16_f32 v230, v230, v231
	global_store_dword v249, v228, s[38:39]
	global_store_dword v250, v230, s[38:39]
	s_add_u32 s38, s38, s55
	s_addc_u32 s39, s39, s56
	s_add_u32 s32, s32, s53
	s_addc_u32 s33, s33, s56
	s_add_u32 s34, s34, s53
	s_addc_u32 s35, s35, s56
	s_add_u32 s36, s36, s54
	s_addc_u32 s37, s37, s56
	s_waitcnt lgkmcnt(0)
	s_barrier
	s_add_i32 s30, s30, 2
	s_cmp_lt_u32 s30, 256
	s_cbranch_scc1 .Lscan_loopA
	s_branch .Lscan_join
